# prologue de-serialisation: weight-prep gain loads (8 per tile, each followed by a full wait) issued together with one wait, in both prep copies
# baseline (speedup 1.0000x reference)
.LBB0_50:
	s_or_b64 exec, exec, s[4:5]
	v_cndmask_b32_e64 v3, 0, 1, s[6:7]
	v_cmp_ne_u32_e64 s[4:5], 1, v3
	s_andn2_b64 vcc, exec, s[6:7]
	s_cbranch_vccnz .LBB0_52
	s_load_dwordx16 s[40:55], s[0:1], 0x0
	v_ashrrev_i32_e32 v39, 31, v38
	s_waitcnt lgkmcnt(0)
	v_lshl_add_u64 v[38:39], v[38:39], 2, s[42:43]
	global_load_dword v46, v[38:39], off
	global_load_dword v48, v[38:39], off offset:64
	global_load_dword v50, v[38:39], off offset:128
	global_load_dword v52, v[38:39], off offset:192
	global_load_dword v54, v[38:39], off offset:256
	global_load_dword v56, v[38:39], off offset:320
	global_load_dword v58, v[38:39], off offset:384
	global_load_dword v60, v[38:39], off offset:448
	s_waitcnt vmcnt(0)
	v_pk_mul_f32 v[34:35], v[34:35], v[46:47] op_sel_hi:[1,0]
	v_pk_mul_f32 v[32:33], v[32:33], v[46:47] op_sel_hi:[1,0]
.LBB0_52:
	v_and_b32_e32 v3, 31, v1
	v_ashrrev_i32_e32 v38, 8, v1
	v_xor_b32_e32 v38, v38, v3
	v_lshlrev_b32_e32 v37, 9, v36
	v_lshlrev_b32_e32 v38, 4, v38
	v_add3_u32 v37, 0, v37, v38
	s_sub_i32 s10, s16, s10
	s_waitcnt vmcnt(0)
	ds_write_b128 v37, v[32:35]
	s_and_b64 vcc, exec, s[4:5]
	v_ashrrev_i32_e32 v37, 31, v36
	s_cbranch_vccnz .LBB0_54
	s_ashr_i32 s11, s10, 31
	v_pk_mul_f32 v[30:31], v[30:31], v[48:49] op_sel_hi:[1,0]
	v_pk_mul_f32 v[28:29], v[28:29], v[48:49] op_sel_hi:[1,0]
.LBB0_54:
	v_add_u32_e32 v32, 16, v36
	v_lshlrev_b32_e32 v33, 9, v32
	v_lshrrev_b32_e32 v32, 3, v32
	v_xor_b32_e32 v32, v32, v3
	v_lshlrev_b32_e32 v32, 4, v32
	v_add3_u32 v32, 0, v33, v32
	s_and_b64 vcc, exec, s[4:5]
	ds_write_b128 v32, v[28:31]
	s_cbranch_vccnz .LBB0_56
	s_ashr_i32 s11, s10, 31
	v_pk_mul_f32 v[26:27], v[26:27], v[50:51] op_sel_hi:[1,0]
	v_pk_mul_f32 v[24:25], v[24:25], v[50:51] op_sel_hi:[1,0]
.LBB0_56:
	v_add_u32_e32 v28, 32, v36
	v_lshlrev_b32_e32 v29, 9, v28
	v_lshrrev_b32_e32 v28, 3, v28
	v_xor_b32_e32 v28, v28, v3
	v_lshlrev_b32_e32 v28, 4, v28
	v_add3_u32 v28, 0, v29, v28
	s_and_b64 vcc, exec, s[4:5]
	ds_write_b128 v28, v[24:27]
	s_cbranch_vccnz .LBB0_58
	s_ashr_i32 s11, s10, 31
	v_pk_mul_f32 v[22:23], v[22:23], v[52:53] op_sel_hi:[1,0]
	v_pk_mul_f32 v[20:21], v[20:21], v[52:53] op_sel_hi:[1,0]
.LBB0_58:
	v_add_u32_e32 v24, 48, v36
	v_lshlrev_b32_e32 v25, 9, v24
	v_lshrrev_b32_e32 v24, 3, v24
	v_xor_b32_e32 v24, v24, v3
	v_lshlrev_b32_e32 v24, 4, v24
	v_add3_u32 v24, 0, v25, v24
	s_and_b64 vcc, exec, s[4:5]
	ds_write_b128 v24, v[20:23]
	s_cbranch_vccnz .LBB0_60
	s_ashr_i32 s11, s10, 31
	v_pk_mul_f32 v[18:19], v[18:19], v[54:55] op_sel_hi:[1,0]
	v_pk_mul_f32 v[16:17], v[16:17], v[54:55] op_sel_hi:[1,0]
.LBB0_60:
	v_add_u32_e32 v20, 64, v36
	v_lshlrev_b32_e32 v21, 9, v20
	v_lshrrev_b32_e32 v20, 3, v20
	v_xor_b32_e32 v20, v20, v3
	v_lshlrev_b32_e32 v20, 4, v20
	v_add3_u32 v20, 0, v21, v20
	s_and_b64 vcc, exec, s[4:5]
	ds_write_b128 v20, v[16:19]
	s_cbranch_vccnz .LBB0_62
	s_ashr_i32 s11, s10, 31
	v_pk_mul_f32 v[14:15], v[14:15], v[56:57] op_sel_hi:[1,0]
	v_pk_mul_f32 v[12:13], v[12:13], v[56:57] op_sel_hi:[1,0]
.LBB0_62:
	v_add_u32_e32 v16, 0x50, v36
	v_lshlrev_b32_e32 v17, 9, v16
	v_lshrrev_b32_e32 v16, 3, v16
	v_xor_b32_e32 v16, v16, v3
	v_lshlrev_b32_e32 v16, 4, v16
	v_add3_u32 v16, 0, v17, v16
	s_and_b64 vcc, exec, s[4:5]
	ds_write_b128 v16, v[12:15]
	s_cbranch_vccnz .LBB0_64
	s_ashr_i32 s11, s10, 31
	v_pk_mul_f32 v[10:11], v[10:11], v[58:59] op_sel_hi:[1,0]
	v_pk_mul_f32 v[8:9], v[8:9], v[58:59] op_sel_hi:[1,0]
.LBB0_64:
	v_add_u32_e32 v12, 0x60, v36
	v_lshlrev_b32_e32 v13, 9, v12
	v_lshrrev_b32_e32 v12, 3, v12
	v_xor_b32_e32 v12, v12, v3
	v_lshlrev_b32_e32 v12, 4, v12
	v_add3_u32 v12, 0, v13, v12
	s_and_b64 vcc, exec, s[6:7]
	ds_write_b128 v12, v[8:11]
	s_cbranch_vccz .LBB0_66
	s_ashr_i32 s11, s10, 31
	v_pk_mul_f32 v[10:11], v[6:7], v[60:61] op_sel_hi:[1,0]
	v_pk_mul_f32 v[8:9], v[4:5], v[60:61] op_sel_hi:[1,0]
	s_cbranch_execnz .LBB0_3
	s_branch .LBB0_2

.LBB0_1141:
	s_or_b64 exec, exec, s[4:5]
	v_cndmask_b32_e64 v1, 0, 1, s[40:41]
	v_cmp_ne_u32_e64 s[4:5], 1, v1
	s_andn2_b64 vcc, exec, s[40:41]
	s_cbranch_vccnz .LBB0_1143
	v_ashrrev_i32_e32 v35, 31, v34
	v_lshl_add_u64 v[34:35], v[34:35], 2, s[36:37]
	global_load_dword v46, v[34:35], off
	v_add_u32_e32 v62, s6, v39
	v_ashrrev_i32_e32 v63, 31, v62
	v_lshl_add_u64 v[62:63], v[62:63], 2, s[36:37]
	global_load_dword v48, v[62:63], off offset:64
	global_load_dword v50, v[62:63], off offset:128
	global_load_dword v52, v[62:63], off offset:192
	global_load_dword v54, v[62:63], off offset:256
	global_load_dword v56, v[62:63], off offset:320
	global_load_dword v58, v[62:63], off offset:384
	global_load_dword v60, v[62:63], off offset:448
	s_waitcnt vmcnt(0)
	v_pk_mul_f32 v[32:33], v[32:33], v[46:47] op_sel_hi:[1,0]
	v_pk_mul_f32 v[30:31], v[30:31], v[46:47] op_sel_hi:[1,0]
.LBB0_1143:
	v_and_b32_e32 v1, 31, v38
	v_ashrrev_i32_e32 v35, 8, v38
	v_xor_b32_e32 v35, v35, v1
	v_lshlrev_b32_e32 v34, 9, v39
	v_lshlrev_b32_e32 v35, 4, v35
	v_add3_u32 v34, 0, v34, v35
	s_waitcnt vmcnt(0)
	ds_write_b128 v34, v[30:33]
	s_and_b64 vcc, exec, s[4:5]
	v_add_u32_e32 v30, 16, v39
	s_cbranch_vccnz .LBB0_1145
	v_pk_mul_f32 v[28:29], v[28:29], v[48:49] op_sel_hi:[1,0]
	v_pk_mul_f32 v[26:27], v[26:27], v[48:49] op_sel_hi:[1,0]
.LBB0_1145:
	v_lshlrev_b32_e32 v31, 9, v30
	v_lshrrev_b32_e32 v30, 3, v30
	v_xor_b32_e32 v30, v30, v1
	v_lshlrev_b32_e32 v30, 4, v30
	v_add3_u32 v30, 0, v31, v30
	ds_write_b128 v30, v[26:29]
	s_and_b64 vcc, exec, s[4:5]
	v_add_u32_e32 v26, 32, v39
	s_cbranch_vccnz .LBB0_1147
	v_pk_mul_f32 v[24:25], v[24:25], v[50:51] op_sel_hi:[1,0]
	v_pk_mul_f32 v[22:23], v[22:23], v[50:51] op_sel_hi:[1,0]
.LBB0_1147:
	v_lshlrev_b32_e32 v27, 9, v26
	v_lshrrev_b32_e32 v26, 3, v26
	v_xor_b32_e32 v26, v26, v1
	v_lshlrev_b32_e32 v26, 4, v26
	v_add3_u32 v26, 0, v27, v26
	ds_write_b128 v26, v[22:25]
	s_and_b64 vcc, exec, s[4:5]
	v_add_u32_e32 v22, 48, v39
	s_cbranch_vccnz .LBB0_1149
	v_pk_mul_f32 v[20:21], v[20:21], v[52:53] op_sel_hi:[1,0]
	v_pk_mul_f32 v[18:19], v[18:19], v[52:53] op_sel_hi:[1,0]
.LBB0_1149:
	v_lshlrev_b32_e32 v23, 9, v22
	v_lshrrev_b32_e32 v22, 3, v22
	v_xor_b32_e32 v22, v22, v1
	v_lshlrev_b32_e32 v22, 4, v22
	v_add3_u32 v22, 0, v23, v22
	ds_write_b128 v22, v[18:21]
	s_and_b64 vcc, exec, s[4:5]
	v_add_u32_e32 v18, 64, v39
	s_cbranch_vccnz .LBB0_1151
	v_pk_mul_f32 v[16:17], v[16:17], v[54:55] op_sel_hi:[1,0]
	v_pk_mul_f32 v[14:15], v[14:15], v[54:55] op_sel_hi:[1,0]
.LBB0_1151:
	v_lshlrev_b32_e32 v19, 9, v18
	v_lshrrev_b32_e32 v18, 3, v18
	v_xor_b32_e32 v18, v18, v1
	v_lshlrev_b32_e32 v18, 4, v18
	v_add3_u32 v18, 0, v19, v18
	ds_write_b128 v18, v[14:17]
	s_and_b64 vcc, exec, s[4:5]
	v_add_u32_e32 v14, 0x50, v39
	s_cbranch_vccnz .LBB0_1153
	v_pk_mul_f32 v[12:13], v[12:13], v[56:57] op_sel_hi:[1,0]
	v_pk_mul_f32 v[10:11], v[10:11], v[56:57] op_sel_hi:[1,0]
.LBB0_1153:
	v_lshlrev_b32_e32 v15, 9, v14
	v_lshrrev_b32_e32 v14, 3, v14
	v_xor_b32_e32 v14, v14, v1
	v_lshlrev_b32_e32 v14, 4, v14
	v_add3_u32 v14, 0, v15, v14
	ds_write_b128 v14, v[10:13]
	s_and_b64 vcc, exec, s[4:5]
	v_add_u32_e32 v10, 0x60, v39
	s_cbranch_vccnz .LBB0_1155
	v_pk_mul_f32 v[8:9], v[8:9], v[58:59] op_sel_hi:[1,0]
	v_pk_mul_f32 v[6:7], v[6:7], v[58:59] op_sel_hi:[1,0]
.LBB0_1155:
	v_lshlrev_b32_e32 v11, 9, v10
	v_lshrrev_b32_e32 v10, 3, v10
	v_xor_b32_e32 v10, v10, v1
	v_lshlrev_b32_e32 v10, 4, v10
	v_add3_u32 v10, 0, v11, v10
	ds_write_b128 v10, v[6:9]
	s_and_b64 vcc, exec, s[4:5]
	v_add_u32_e32 v6, 0x70, v39
	s_cbranch_vccnz .LBB0_1088
	v_pk_mul_f32 v[4:5], v[4:5], v[60:61] op_sel_hi:[1,0]
	v_pk_mul_f32 v[2:3], v[2:3], v[60:61] op_sel_hi:[1,0]
	s_branch .LBB0_1088
